# grid barrier: the XCD leader issues its buffer_inv after signalling the global counter (its local-arrival polls no longer queue behind the invalidate)
# speedup vs baseline: 1.0036x; 1.0025x over previous
.LBB0_31:
	s_lshl_b32 s3, s3, 8
	s_add_u32 s10, s6, s3
	s_addc_u32 s11, s7, 0
	v_mov_b32_e32 v0, 0x23fc8
	ds_read2_b32 v[4:5], v0 offset1:1
	v_mov_b32_e32 v6, 1
	v_mov_b32_e32 v7, 0x1000
	global_atomic_add v7, v6, s[10:11] offset:1024
	s_waitcnt lgkmcnt(0)
	v_add_u32_e32 v8, 1, v5
	v_mov_b32_e32 v9, 0x23fcc
	ds_write_b32 v9, v8
	v_mul_lo_u32 v10, v8, v3
	v_mul_lo_u32 v11, v8, v2
	s_nop 0
	v_cmp_ne_u32_e32 vcc, 0, v4
	s_cbranch_vccnz .Lnb_nl_r
	s_mov_b32 s3, 0

.Lnb_loc_done_r:
	s_nop 0
	s_waitcnt vmcnt(0)
	v_mov_b32_e32 v6, 1
	v_mov_b32_e32 v12, 0x3400
	global_atomic_add v12, v6, s[6:7]
	buffer_inv sc1
	s_branch .Lnb_poll_top_r
.Lnb_nl_r:
	buffer_inv sc1
.Lnb_poll_top_r:
	v_mov_b32_e32 v12, 0x3400
	s_mov_b32 s3, 0

.LBB0_664:
	s_lshl_b32 s2, s2, 8
	s_add_u32 s10, s6, s2
	s_addc_u32 s11, s7, 0
	v_mov_b32_e32 v0, 0x23fc8
	ds_read2_b32 v[4:5], v0 offset1:1
	v_mov_b32_e32 v6, 1
	v_mov_b32_e32 v7, 0x1000
	global_atomic_add v7, v6, s[10:11] offset:1024
	s_waitcnt lgkmcnt(0)
	v_add_u32_e32 v8, 1, v5
	v_mov_b32_e32 v9, 0x23fcc
	ds_write_b32 v9, v8
	v_mul_lo_u32 v10, v8, v3
	v_mul_lo_u32 v11, v8, v2
	s_nop 0
	v_cmp_ne_u32_e32 vcc, 0, v4
	s_cbranch_vccnz .Lnb_nl_m
	s_mov_b32 s2, 0

.Lnb_nl_m:
	buffer_inv sc1
.Lnb_poll_top_m:
	v_mov_b32_e32 v12, 0x3400
	s_mov_b32 s2, 0
